# side_gemm1: rotate the K-batch order per workgroup ((blockIdx>>3)&3) so the CUs of one XCD do not all read the same W_dt lines at the same time
# speedup vs baseline: 1.0024x; 1.0024x over previous
; #define GAS __attribute__((address_space(1)))
; __device__ __forceinline__ f32x4 mfma16(const bf16x8& a, const bf16x8& b, const f32x4& c) { return __builtin_amdgcn_mfma_f32_16x16x32_bf16(a, b, c, 0, 0, 0); }
; template <class F> __device__ __forceinline__ void skinny_tile(const GAS bf16* A, int lda, const GAS bf16* Bt, int K, int n0, int lane, F&& epi) {
;     ...
;     for (int k = 0; k < K; k += 256) {
; #pragma unroll
;         for (int i = 0; i < 4; ++i) { a2[i] = *(const GAS bf16x8*)(ap + k + 128 + i * 32); b2[i] = *(const GAS bf16x8*)(bp + k + 128 + i * 32); }
; #pragma unroll
;         for (int i = 0; i < 4; i += 2) { acc0 = mfma16(a[i], bb[i], acc0); acc1 = mfma16(a[i + 1], bb[i + 1], acc1); }
;         if (k + 256 < K) {
; #pragma unroll
;             for (int i = 0; i < 4; ++i) { a[i] = *(const GAS bf16x8*)(ap + k + 256 + i * 32); bb[i] = *(const GAS bf16x8*)(bp + k + 256 + i * 32); } }
; #pragma unroll
;         for (int i = 0; i < 4; i += 2) { acc0 = mfma16(a2[i], b2[i], acc0); acc1 = mfma16(a2[i + 1], b2[i + 1], acc1); } }
; #pragma unroll
;     for (int j = 0; j < 4; ++j) epi(fq * 4 + j, j, n0 + fr, acc0[j] + acc1[j]);
; __device__ __forceinline__ void side_gemm1(const Params& P, int seg) {
;     ...
;     for (int it = gw; it < nrt * 4; it += NGW) { const int rt = it >> 2, r0 = (rt < RS / 16) ? rt * 16 : RS + 48;
;         skinny_tile(xb + (size_t)r0 * DM, DM, Wt + (size_t)NPROJ * DM, DM, (it & 3) * 16, lane, [&](int row, int j, int col, float v) {
;             const float t = v * rstd1[r0 + row] + P.dt_bias[col]; dtv[(size_t)(r0 + row) * 64 + col] = (t > 20.f) ? t : log1pf(__expf(t)); }); }
.Lsg1_new:
	s_mov_b32 s100, 0
	s_mov_b32 s101, 0
	v_lshrrev_b32_e32 v116, 6, v172
	v_and_b32_e32 v117, 3, v116
	v_lshlrev_b32_e32 v18, 10, v117
	v_mov_b32_e32 v19, 0
	v_lshl_add_u64 v[212:213], v[4:5], 0, v[18:19]
	v_and_b32_e32 v214, 48, v172
	v_lshl_add_u32 v214, v28, 12, v214
	v_add_u32_e32 v214, v214, v18
	s_add_u32 s46, s40, 0x5000000
	s_addc_u32 s47, s41, 0
	s_add_u32 s48, s46, 0x10000
	s_addc_u32 s49, s47, 0
	s_add_u32 s50, s46, 0x20000
	s_addc_u32 s51, s47, 0
	s_add_u32 s52, s46, 0x30000
	s_addc_u32 s53, s47, 0
	s_lshr_b32 s100, s2, 3
	s_add_i32 s100, s100, 0
	s_and_b32 s100, s100, 3
	s_lshl_b32 s100, s100, 8
	v_lshl_add_u64 v[220:221], v[212:213], 0, s[100:101]
	v_add_u32_e32 v222, s100, v214
	global_load_dwordx4 v[36:39], v[220:221], off
	global_load_dwordx4 v[40:43], v[220:221], off offset:64
	global_load_dwordx4 v[44:47], v[220:221], off offset:128
	global_load_dwordx4 v[48:51], v[220:221], off offset:192
	global_load_dwordx4 v[52:55], v222, s[46:47]
	global_load_dwordx4 v[56:59], v222, s[46:47] offset:64
	global_load_dwordx4 v[60:63], v222, s[46:47] offset:128
	global_load_dwordx4 v[64:67], v222, s[46:47] offset:192
	global_load_dwordx4 v[68:71], v222, s[48:49]
	global_load_dwordx4 v[72:75], v222, s[48:49] offset:64
	global_load_dwordx4 v[76:79], v222, s[48:49] offset:128
	global_load_dwordx4 v[80:83], v222, s[48:49] offset:192
	global_load_dwordx4 v[84:87], v222, s[50:51]
	global_load_dwordx4 v[88:91], v222, s[50:51] offset:64
	global_load_dwordx4 v[92:95], v222, s[50:51] offset:128
	global_load_dwordx4 v[96:99], v222, s[50:51] offset:192
	global_load_dwordx4 v[100:103], v222, s[52:53]
	global_load_dwordx4 v[104:107], v222, s[52:53] offset:64
	global_load_dwordx4 v[108:111], v222, s[52:53] offset:128
	global_load_dwordx4 v[112:115], v222, s[52:53] offset:192
	s_lshr_b32 s100, s2, 3
	s_add_i32 s100, s100, 1
	s_and_b32 s100, s100, 3
	s_lshl_b32 s100, s100, 8
	v_lshl_add_u64 v[220:221], v[212:213], 0, s[100:101]
	v_add_u32_e32 v222, s100, v214
	global_load_dwordx4 v[120:123], v[220:221], off
	global_load_dwordx4 v[124:127], v[220:221], off offset:64
	global_load_dwordx4 v[128:131], v[220:221], off offset:128
	global_load_dwordx4 v[132:135], v[220:221], off offset:192
	global_load_dwordx4 v[136:139], v222, s[46:47]
	global_load_dwordx4 v[140:143], v222, s[46:47] offset:64
	global_load_dwordx4 v[144:147], v222, s[46:47] offset:128
	global_load_dwordx4 v[148:151], v222, s[46:47] offset:192
	global_load_dwordx4 v[152:155], v222, s[48:49]
	global_load_dwordx4 v[156:159], v222, s[48:49] offset:64
	global_load_dwordx4 v[160:163], v222, s[48:49] offset:128
	global_load_dwordx4 v[164:167], v222, s[48:49] offset:192
	global_load_dwordx4 v[168:171], v222, s[50:51]
	global_load_dwordx4 v[184:187], v222, s[50:51] offset:64
	global_load_dwordx4 v[188:191], v222, s[50:51] offset:128
	global_load_dwordx4 v[192:195], v222, s[50:51] offset:192
	global_load_dwordx4 v[196:199], v222, s[52:53]
	global_load_dwordx4 v[200:203], v222, s[52:53] offset:64
	global_load_dwordx4 v[204:207], v222, s[52:53] offset:128
	global_load_dwordx4 v[208:211], v222, s[52:53] offset:192
	s_waitcnt vmcnt(20)
	v_mfma_f32_16x16x32_bf16 v[4:7], v[36:39], v[52:55], 0
	v_mfma_f32_16x16x32_bf16 v[8:11], v[36:39], v[68:71], 0
	v_mfma_f32_16x16x32_bf16 v[20:23], v[36:39], v[84:87], 0
	v_mfma_f32_16x16x32_bf16 v[32:35], v[36:39], v[100:103], 0
	v_mfma_f32_16x16x32_bf16 v[4:7], v[40:43], v[56:59], v[4:7]
	v_mfma_f32_16x16x32_bf16 v[8:11], v[40:43], v[72:75], v[8:11]
	v_mfma_f32_16x16x32_bf16 v[20:23], v[40:43], v[88:91], v[20:23]
	v_mfma_f32_16x16x32_bf16 v[32:35], v[40:43], v[104:107], v[32:35]
	v_mfma_f32_16x16x32_bf16 v[4:7], v[44:47], v[60:63], v[4:7]
	v_mfma_f32_16x16x32_bf16 v[8:11], v[44:47], v[76:79], v[8:11]
	v_mfma_f32_16x16x32_bf16 v[20:23], v[44:47], v[92:95], v[20:23]
	v_mfma_f32_16x16x32_bf16 v[32:35], v[44:47], v[108:111], v[32:35]
	v_mfma_f32_16x16x32_bf16 v[4:7], v[48:51], v[64:67], v[4:7]
	v_mfma_f32_16x16x32_bf16 v[8:11], v[48:51], v[80:83], v[8:11]
	v_mfma_f32_16x16x32_bf16 v[20:23], v[48:51], v[96:99], v[20:23]
	v_mfma_f32_16x16x32_bf16 v[32:35], v[48:51], v[112:115], v[32:35]
	s_lshr_b32 s100, s2, 3
	s_add_i32 s100, s100, 2
	s_and_b32 s100, s100, 3
	s_lshl_b32 s100, s100, 8
	v_lshl_add_u64 v[220:221], v[212:213], 0, s[100:101]
	v_add_u32_e32 v222, s100, v214
	global_load_dwordx4 v[36:39], v[220:221], off
	global_load_dwordx4 v[40:43], v[220:221], off offset:64
	global_load_dwordx4 v[44:47], v[220:221], off offset:128
	global_load_dwordx4 v[48:51], v[220:221], off offset:192
	global_load_dwordx4 v[52:55], v222, s[46:47]
	global_load_dwordx4 v[56:59], v222, s[46:47] offset:64
	global_load_dwordx4 v[60:63], v222, s[46:47] offset:128
	global_load_dwordx4 v[64:67], v222, s[46:47] offset:192
	global_load_dwordx4 v[68:71], v222, s[48:49]
	global_load_dwordx4 v[72:75], v222, s[48:49] offset:64
	global_load_dwordx4 v[76:79], v222, s[48:49] offset:128
	global_load_dwordx4 v[80:83], v222, s[48:49] offset:192
	global_load_dwordx4 v[84:87], v222, s[50:51]
	global_load_dwordx4 v[88:91], v222, s[50:51] offset:64
	global_load_dwordx4 v[92:95], v222, s[50:51] offset:128
	global_load_dwordx4 v[96:99], v222, s[50:51] offset:192
	global_load_dwordx4 v[100:103], v222, s[52:53]
	global_load_dwordx4 v[104:107], v222, s[52:53] offset:64
	global_load_dwordx4 v[108:111], v222, s[52:53] offset:128
	global_load_dwordx4 v[112:115], v222, s[52:53] offset:192
	s_waitcnt vmcnt(20)
; #define GAS __attribute__((address_space(1)))
; template <class F> __device__ __forceinline__ void skinny_tile(const GAS bf16* A, int lda, const GAS bf16* Bt, int K, int n0, int lane, F&& epi) {
;     ...
;     for (int k = 0; k < K; k += 256) {
; #pragma unroll
;         for (int i = 0; i < 4; ++i) { a2[i] = *(const GAS bf16x8*)(ap + k + 128 + i * 32); b2[i] = *(const GAS bf16x8*)(bp + k + 128 + i * 32); }
; #pragma unroll
;         for (int i = 0; i < 4; i += 2) { acc0 = mfma16(a[i], bb[i], acc0); acc1 = mfma16(a[i + 1], bb[i + 1], acc1); }
;         if (k + 256 < K) {
; #pragma unroll
;             for (int i = 0; i < 4; ++i) { a[i] = *(const GAS bf16x8*)(ap + k + 256 + i * 32); bb[i] = *(const GAS bf16x8*)(bp + k + 256 + i * 32); } }
; #pragma unroll
;         for (int i = 0; i < 4; i += 2) { acc0 = mfma16(a2[i], b2[i], acc0); acc1 = mfma16(a2[i + 1], b2[i + 1], acc1); } }
; #pragma unroll
;     for (int j = 0; j < 4; ++j) epi(fq * 4 + j, j, n0 + fr, acc0[j] + acc1[j]);
; }
; template <class F> __device__ __forceinline__ void skinny_tile_sk(const GAS bf16* A, int lda, const GAS bf16* Bt, int K, int n0, int wave, int lane, float* red, F&& epi) {
;     const int fr = lane & 15, fq = lane >> 4, kc = K >> 3;
;     const GAS bf16* ap = A + (size_t)fr * lda + wave * kc + fq * 8; const GAS bf16* bp = Bt + (size_t)(n0 + fr) * K + wave * kc + fq * 8;
;     f32x4 acc0 = {0.f, 0.f, 0.f, 0.f}, acc1 = {0.f, 0.f, 0.f, 0.f};
;     for (int k = 0; k < kc; k += 256) { bf16x8 a[8], bb[8];
; #pragma unroll
;         for (int i = 0; i < 8; ++i) { a[i] = *(const GAS bf16x8*)(ap + k + i * 32); bb[i] = *(const GAS bf16x8*)(bp + k + i * 32); }
; #pragma unroll
;         for (int i = 0; i < 8; i += 2) { acc0 = mfma16(a[i], bb[i], acc0); acc1 = mfma16(a[i + 1], bb[i + 1], acc1); } }
;     __syncthreads();
;     *(f32x4*)(red + wave * 256 + lane * 4) = acc0 + acc1;
;     __syncthreads();
;     if (wave == 0) { f32x4 s = {0.f, 0.f, 0.f, 0.f};
; #pragma unroll
;         for (int w = 0; w < 8; ++w) s += *(const f32x4*)(red + w * 256 + lane * 4);
; __device__ __forceinline__ void side_gemm1(const Params& P, int seg) {
;     ...
;     for (int it = gw; it < nrt * 4; it += NGW) { const int rt = it >> 2, r0 = (rt < RS / 16) ? rt * 16 : RS + 48;
;         skinny_tile(xb + (size_t)r0 * DM, DM, Wt + (size_t)NPROJ * DM, DM, (it & 3) * 16, lane, [&](int row, int j, int col, float v) {
	v_mfma_f32_16x16x32_bf16 v[4:7], v[120:123], v[136:139], v[4:7]
	v_mfma_f32_16x16x32_bf16 v[8:11], v[120:123], v[152:155], v[8:11]
	v_mfma_f32_16x16x32_bf16 v[20:23], v[120:123], v[168:171], v[20:23]
	v_mfma_f32_16x16x32_bf16 v[32:35], v[120:123], v[196:199], v[32:35]
	v_mfma_f32_16x16x32_bf16 v[4:7], v[124:127], v[140:143], v[4:7]
	v_mfma_f32_16x16x32_bf16 v[8:11], v[124:127], v[156:159], v[8:11]
	v_mfma_f32_16x16x32_bf16 v[20:23], v[124:127], v[184:187], v[20:23]
	v_mfma_f32_16x16x32_bf16 v[32:35], v[124:127], v[200:203], v[32:35]
	v_mfma_f32_16x16x32_bf16 v[4:7], v[128:131], v[144:147], v[4:7]
	v_mfma_f32_16x16x32_bf16 v[8:11], v[128:131], v[160:163], v[8:11]
	v_mfma_f32_16x16x32_bf16 v[20:23], v[128:131], v[188:191], v[20:23]
	v_mfma_f32_16x16x32_bf16 v[32:35], v[128:131], v[204:207], v[32:35]
	v_mfma_f32_16x16x32_bf16 v[4:7], v[132:135], v[148:151], v[4:7]
	v_mfma_f32_16x16x32_bf16 v[8:11], v[132:135], v[164:167], v[8:11]
	v_mfma_f32_16x16x32_bf16 v[20:23], v[132:135], v[192:195], v[20:23]
	v_mfma_f32_16x16x32_bf16 v[32:35], v[132:135], v[208:211], v[32:35]
	s_lshr_b32 s100, s2, 3
	s_add_i32 s100, s100, 3
	s_and_b32 s100, s100, 3
	s_lshl_b32 s100, s100, 8
	v_lshl_add_u64 v[220:221], v[212:213], 0, s[100:101]
	v_add_u32_e32 v222, s100, v214
	global_load_dwordx4 v[120:123], v[220:221], off
	global_load_dwordx4 v[124:127], v[220:221], off offset:64
	global_load_dwordx4 v[128:131], v[220:221], off offset:128
	global_load_dwordx4 v[132:135], v[220:221], off offset:192
	global_load_dwordx4 v[136:139], v222, s[46:47]
	global_load_dwordx4 v[140:143], v222, s[46:47] offset:64
	global_load_dwordx4 v[144:147], v222, s[46:47] offset:128
	global_load_dwordx4 v[148:151], v222, s[46:47] offset:192
	global_load_dwordx4 v[152:155], v222, s[48:49]
	global_load_dwordx4 v[156:159], v222, s[48:49] offset:64
	global_load_dwordx4 v[160:163], v222, s[48:49] offset:128
	global_load_dwordx4 v[164:167], v222, s[48:49] offset:192
	global_load_dwordx4 v[168:171], v222, s[50:51]
	global_load_dwordx4 v[184:187], v222, s[50:51] offset:64
	global_load_dwordx4 v[188:191], v222, s[50:51] offset:128
	global_load_dwordx4 v[192:195], v222, s[50:51] offset:192
	global_load_dwordx4 v[196:199], v222, s[52:53]
	global_load_dwordx4 v[200:203], v222, s[52:53] offset:64
	global_load_dwordx4 v[204:207], v222, s[52:53] offset:128
	global_load_dwordx4 v[208:211], v222, s[52:53] offset:192
	s_waitcnt vmcnt(20)
	v_mfma_f32_16x16x32_bf16 v[4:7], v[36:39], v[52:55], v[4:7]
	v_mfma_f32_16x16x32_bf16 v[8:11], v[36:39], v[68:71], v[8:11]
	v_mfma_f32_16x16x32_bf16 v[20:23], v[36:39], v[84:87], v[20:23]
	v_mfma_f32_16x16x32_bf16 v[32:35], v[36:39], v[100:103], v[32:35]
	v_mfma_f32_16x16x32_bf16 v[4:7], v[40:43], v[56:59], v[4:7]
	v_mfma_f32_16x16x32_bf16 v[8:11], v[40:43], v[72:75], v[8:11]
	v_mfma_f32_16x16x32_bf16 v[20:23], v[40:43], v[88:91], v[20:23]
	v_mfma_f32_16x16x32_bf16 v[32:35], v[40:43], v[104:107], v[32:35]
	v_mfma_f32_16x16x32_bf16 v[4:7], v[44:47], v[60:63], v[4:7]
	v_mfma_f32_16x16x32_bf16 v[8:11], v[44:47], v[76:79], v[8:11]
	v_mfma_f32_16x16x32_bf16 v[20:23], v[44:47], v[92:95], v[20:23]
	v_mfma_f32_16x16x32_bf16 v[32:35], v[44:47], v[108:111], v[32:35]
	v_mfma_f32_16x16x32_bf16 v[4:7], v[48:51], v[64:67], v[4:7]
	v_mfma_f32_16x16x32_bf16 v[8:11], v[48:51], v[80:83], v[8:11]
	v_mfma_f32_16x16x32_bf16 v[20:23], v[48:51], v[96:99], v[20:23]
	v_mfma_f32_16x16x32_bf16 v[32:35], v[48:51], v[112:115], v[32:35]
	s_waitcnt vmcnt(0)
	v_mfma_f32_16x16x32_bf16 v[4:7], v[120:123], v[136:139], v[4:7]
	v_mfma_f32_16x16x32_bf16 v[8:11], v[120:123], v[152:155], v[8:11]
	v_mfma_f32_16x16x32_bf16 v[20:23], v[120:123], v[168:171], v[20:23]
	v_mfma_f32_16x16x32_bf16 v[32:35], v[120:123], v[196:199], v[32:35]
	v_mfma_f32_16x16x32_bf16 v[4:7], v[124:127], v[140:143], v[4:7]
	v_mfma_f32_16x16x32_bf16 v[8:11], v[124:127], v[156:159], v[8:11]
	v_mfma_f32_16x16x32_bf16 v[20:23], v[124:127], v[184:187], v[20:23]
	v_mfma_f32_16x16x32_bf16 v[32:35], v[124:127], v[200:203], v[32:35]
	v_mfma_f32_16x16x32_bf16 v[4:7], v[128:131], v[144:147], v[4:7]
	v_mfma_f32_16x16x32_bf16 v[8:11], v[128:131], v[160:163], v[8:11]
	v_mfma_f32_16x16x32_bf16 v[20:23], v[128:131], v[188:191], v[20:23]
	v_mfma_f32_16x16x32_bf16 v[32:35], v[128:131], v[204:207], v[32:35]
	v_mfma_f32_16x16x32_bf16 v[4:7], v[132:135], v[148:151], v[4:7]
	v_mfma_f32_16x16x32_bf16 v[8:11], v[132:135], v[164:167], v[8:11]
	v_mfma_f32_16x16x32_bf16 v[20:23], v[132:135], v[192:195], v[20:23]
	v_mfma_f32_16x16x32_bf16 v[32:35], v[132:135], v[208:211], v[32:35]
	v_and_b32_e32 v18, 63, v172
	v_lshlrev_b32_e32 v18, 4, v18
	v_lshl_add_u32 v19, v116, 12, v18
	s_nop 5
	ds_write_b128 v19, v[4:7] offset:0
	ds_write_b128 v19, v[8:11] offset:1024
	ds_write_b128 v19, v[20:23] offset:2048
	ds_write_b128 v19, v[32:35] offset:3072
	s_waitcnt lgkmcnt(0)
	s_barrier
	v_lshrrev_b32_e32 v19, 2, v116
	v_lshl_add_u32 v19, v19, 14, v18
	v_lshl_add_u32 v19, v117, 10, v19
	ds_read_b128 v[36:39], v19 offset:0
	ds_read_b128 v[40:43], v19 offset:4096
	ds_read_b128 v[44:47], v19 offset:8192
	ds_read_b128 v[48:51], v19 offset:12288
	s_waitcnt lgkmcnt(0)
	v_add_f32_e32 v4, v36, v40
	v_add_f32_e32 v8, v44, v48
	v_add_f32_e32 v5, v37, v41
	v_add_f32_e32 v9, v45, v49
	v_add_f32_e32 v6, v38, v42
	v_add_f32_e32 v10, v46, v50
	v_add_f32_e32 v7, v39, v43
	v_add_f32_e32 v11, v47, v51
	v_add_f32_e32 v4, v4, v8
	v_add_f32_e32 v5, v5, v9
	v_add_f32_e32 v6, v6, v10
	v_add_f32_e32 v7, v7, v11
	v_mov_b32_e32 v8, 0
	v_mov_b32_e32 v9, 0
	v_mov_b32_e32 v10, 0
	v_mov_b32_e32 v11, 0
	v_or_b32_e32 v16, v16, v29
	v_lshlrev_b32_e32 v174, 2, v17
	v_ashrrev_i32_e32 v17, 31, v16
	v_lshl_add_u64 v[18:19], v[16:17], 2, s[14:15]
	s_mov_b32 s100, 0
	s_branch .Lsg1_join
